# kmax pre-pass: each wave takes one 64-token slice of a (b,g,branch,quarter) task instead of looping over 8 slices serially (2048 micro-tasks over 1536 waves)
# speedup vs baseline: 1.0063x; 1.0063x over previous
.LBB0_465:
	s_cmp_gt_i32 s97, 63
	s_mov_b64 s[0:1], -1
	s_cbranch_scc0 .LBB0_491
	s_mov_b32 s48, 0
	s_mov_b32 s49, 0
	s_mov_b32 s32, 0
	s_movk_i32 s96, 0x580
	s_sub_i32 s30, s97, 64
	v_mov_b32_e32 v0, v224
	s_lshl_b32 s29, s30, 3
	s_waitcnt lgkmcnt(0)
	v_ashrrev_i32_e32 v1, 6, v0
	s_sub_i32 s31, s94, 64
	v_add_u32_e32 v4, s29, v1
	s_movk_i32 s0, 0x800
	s_lshl_b32 s28, s31, 3
	v_cmp_gt_i32_e32 vcc, s0, v4
	s_and_saveexec_b64 s[0:1], vcc
	s_cbranch_execz .LBB0_473
	v_and_b32_e32 v5, 63, v0
	v_mbcnt_lo_u32_b32 v0, -1, 0
	v_mbcnt_hi_u32_b32 v0, -1, v0
	v_and_b32_e32 v1, 64, v0
	v_add_u32_e32 v1, 64, v1
	v_xor_b32_e32 v2, 1, v0
	v_cmp_lt_i32_e64 s[2:3], v2, v1
	s_lshl_b32 s6, s94, 12
	s_lshl_b32 s7, s94, 6
	v_cndmask_b32_e64 v2, v0, v2, s[2:3]
	v_lshlrev_b32_e32 v6, 2, v2
	v_xor_b32_e32 v2, 2, v0
	v_cmp_lt_i32_e64 s[2:3], v2, v1
	v_cmp_eq_u32_e32 vcc, 0, v5
	v_lshlrev_b32_e32 v12, 9, v4
	v_cndmask_b32_e64 v2, v0, v2, s[2:3]
	v_lshlrev_b32_e32 v7, 2, v2
	v_xor_b32_e32 v2, 4, v0
	v_cmp_lt_i32_e64 s[2:3], v2, v1
	s_add_i32 s6, s6, 0xfffc0000
	v_lshlrev_b32_e32 v13, 3, v4
	v_cndmask_b32_e64 v2, v0, v2, s[2:3]
	v_lshlrev_b32_e32 v8, 2, v2
	v_xor_b32_e32 v2, 8, v0
	v_cmp_lt_i32_e64 s[2:3], v2, v1
	s_addk_i32 s7, 0xf000
	s_mov_b64 s[4:5], 0
	v_cndmask_b32_e64 v2, v0, v2, s[2:3]
	v_lshlrev_b32_e32 v9, 2, v2
	v_xor_b32_e32 v2, 16, v0
	v_cmp_lt_i32_e64 s[2:3], v2, v1
	s_movk_i32 s8, 0x600
	v_mov_b32_e32 v14, 0x1800
	v_cndmask_b32_e64 v2, v0, v2, s[2:3]
	v_lshlrev_b32_e32 v10, 2, v2
	v_xor_b32_e32 v2, 32, v0
	v_cmp_lt_i32_e64 s[2:3], v2, v1
	v_mov_b32_e32 v15, 0x1600
	s_mov_b32 s9, 0xe00000
	v_cndmask_b32_e64 v0, v0, v2, s[2:3]
	v_lshlrev_b32_e32 v11, 2, v0
	s_movk_i32 s10, 0x80
	v_mov_b32_e32 v1, 0
	s_movk_i32 s11, 0x7ff
	s_branch .LBB0_469

.LBB0_469:
	v_ashrrev_i32_e32 v88, 3, v4
	v_and_b32_e32 v91, 7, v4
	v_lshlrev_b32_e32 v89, 9, v88
	v_lshlrev_b32_e32 v90, 3, v88
	v_and_or_b32 v0, v89, s8, v5
	v_and_b32_e32 v16, 4, v88
	v_mul_hi_u32_u24_e32 v3, 0x1c00, v0
	s_waitcnt lgkmcnt(0)
	v_mul_u32_u24_e32 v2, 0x1c00, v0
	v_ashrrev_i32_e32 v0, 4, v88
	v_cmp_eq_u32_e64 s[2:3], 0, v16
	s_nop 1
	v_cndmask_b32_e64 v16, v14, v15, s[2:3]
	v_mad_i64_i32 v[2:3], s[2:3], v0, s9, v[2:3]
	v_lshlrev_b32_e32 v0, 1, v90
	v_and_or_b32 v0, v0, s10, v16
	v_lshl_add_u64 v[2:3], v[2:3], 0, v[0:1]
	v_lshl_add_u64 v[2:3], s[80:81], 0, v[2:3]
	v_readfirstlane_b32 s2, v91
	s_mul_i32 s2, s2, 0x70000
	s_mov_b32 s3, 0
	v_mov_b32_e32 v0, 0
.LBB0_470:
	v_lshl_add_u64 v[44:45], v[2:3], 0, s[2:3]
	global_load_dwordx4 v[16:19], v[44:45], off
	global_load_dwordx4 v[20:23], v[44:45], off offset:16
	global_load_dwordx4 v[24:27], v[44:45], off offset:32
	global_load_dwordx4 v[28:31], v[44:45], off offset:48
	global_load_dwordx4 v[32:35], v[44:45], off offset:64
	global_load_dwordx4 v[36:39], v[44:45], off offset:80
	global_load_dwordx4 v[40:43], v[44:45], off offset:96
	s_nop 0
	global_load_dwordx4 v[44:47], v[44:45], off offset:112
	s_add_u32 s2, s2, 0x70000
	v_max_f32_e32 v0, v0, v0
	s_addc_u32 s3, s3, 0
	s_cmp_lg_u32 s2, 0x380000
	s_waitcnt vmcnt(7)
	v_and_b32_e32 v49, 0xffff0000, v16
	v_and_b32_e32 v51, 0xffff0000, v17
	v_lshlrev_b32_e32 v48, 16, v16
	v_lshlrev_b32_e32 v50, 16, v17
	v_lshlrev_b32_e32 v52, 16, v18
	v_and_b32_e32 v53, 0xffff0000, v18
	v_lshlrev_b32_e32 v54, 16, v19
	v_and_b32_e32 v55, 0xffff0000, v19
	s_waitcnt vmcnt(6)
	v_lshlrev_b32_e32 v60, 16, v22
	v_and_b32_e32 v61, 0xffff0000, v22
	v_lshlrev_b32_e32 v62, 16, v23
	v_and_b32_e32 v63, 0xffff0000, v23
	s_waitcnt vmcnt(5)
	v_lshlrev_b32_e32 v64, 16, v24
	v_and_b32_e32 v65, 0xffff0000, v24
	v_lshlrev_b32_e32 v66, 16, v25
	v_and_b32_e32 v67, 0xffff0000, v25
	v_lshlrev_b32_e32 v68, 16, v26
	v_and_b32_e32 v69, 0xffff0000, v26
	v_lshlrev_b32_e32 v70, 16, v27
	v_and_b32_e32 v71, 0xffff0000, v27
	s_waitcnt vmcnt(4)
	v_lshlrev_b32_e32 v76, 16, v30
	v_and_b32_e32 v77, 0xffff0000, v30
	v_lshlrev_b32_e32 v78, 16, v31
	v_and_b32_e32 v79, 0xffff0000, v31
	s_waitcnt vmcnt(2)
	v_and_b32_e32 v19, 0xffff0000, v37
	v_and_b32_e32 v18, 0xffff0000, v36
	v_and_b32_e32 v23, 0xffff0000, v39
	v_and_b32_e32 v22, 0xffff0000, v38
	s_waitcnt vmcnt(1)
	v_lshlrev_b32_e32 v25, 16, v41
	v_lshlrev_b32_e32 v24, 16, v40
	v_and_b32_e32 v27, 0xffff0000, v41
	v_and_b32_e32 v26, 0xffff0000, v40
	v_and_b32_e32 v31, 0xffff0000, v43
	v_and_b32_e32 v30, 0xffff0000, v42
	v_mul_f32_e32 v40, v49, v49
	v_mul_f32_e32 v41, v51, v51
	v_lshlrev_b32_e32 v56, 16, v20
	v_and_b32_e32 v57, 0xffff0000, v20
	v_lshlrev_b32_e32 v58, 16, v21
	v_and_b32_e32 v59, 0xffff0000, v21
	v_lshlrev_b32_e32 v72, 16, v28
	v_and_b32_e32 v73, 0xffff0000, v28
	v_lshlrev_b32_e32 v74, 16, v29
	v_and_b32_e32 v75, 0xffff0000, v29
	v_lshlrev_b32_e32 v17, 16, v37
	v_lshlrev_b32_e32 v16, 16, v36
	v_lshlrev_b32_e32 v21, 16, v39
	v_lshlrev_b32_e32 v20, 16, v38
	v_lshlrev_b32_e32 v29, 16, v43
	v_lshlrev_b32_e32 v28, 16, v42
	v_mul_f32_e32 v42, v53, v53
	v_pk_mul_f32 v[18:19], v[18:19], v[18:19]
	v_pk_mul_f32 v[22:23], v[22:23], v[22:23]
	v_pk_mul_f32 v[30:31], v[30:31], v[30:31]
	v_fmac_f32_e32 v40, v48, v48
	v_fmac_f32_e32 v41, v50, v50
	v_mul_f32_e32 v43, v55, v55
	v_fmac_f32_e32 v42, v52, v52
	v_pk_fma_f32 v[16:17], v[16:17], v[16:17], v[18:19]
	v_pk_fma_f32 v[18:19], v[20:21], v[20:21], v[22:23]
	v_pk_fma_f32 v[22:23], v[28:29], v[28:29], v[30:31]
	v_add_f32_e32 v28, v40, v41
	v_lshlrev_b32_e32 v80, 16, v32
	v_and_b32_e32 v81, 0xffff0000, v32
	v_lshlrev_b32_e32 v84, 16, v34
	v_and_b32_e32 v85, 0xffff0000, v34
	s_waitcnt vmcnt(0)
	v_lshlrev_b32_e32 v32, 16, v44
	v_and_b32_e32 v34, 0xffff0000, v44
	v_mul_f32_e32 v44, v57, v57
	v_fmac_f32_e32 v43, v54, v54
	v_add_f32_e32 v28, v42, v28
	v_lshlrev_b32_e32 v82, 16, v33
	v_and_b32_e32 v83, 0xffff0000, v33
	v_lshlrev_b32_e32 v86, 16, v35
	v_and_b32_e32 v87, 0xffff0000, v35
	v_lshlrev_b32_e32 v33, 16, v45
	v_and_b32_e32 v35, 0xffff0000, v45
	v_mul_f32_e32 v45, v59, v59
	v_fmac_f32_e32 v44, v56, v56
	v_add_f32_e32 v28, v43, v28
	v_lshlrev_b32_e32 v36, 16, v46
	v_and_b32_e32 v38, 0xffff0000, v46
	v_mul_f32_e32 v46, v61, v61
	v_fmac_f32_e32 v45, v58, v58
	v_add_f32_e32 v28, v44, v28
	v_lshlrev_b32_e32 v37, 16, v47
	v_and_b32_e32 v39, 0xffff0000, v47
	v_mul_f32_e32 v47, v63, v63
	v_fmac_f32_e32 v46, v60, v60
	v_add_f32_e32 v28, v45, v28
	v_mul_f32_e32 v49, v65, v65
	v_fmac_f32_e32 v47, v62, v62
	v_add_f32_e32 v28, v46, v28
	v_mul_f32_e32 v51, v67, v67
	v_fmac_f32_e32 v49, v64, v64
	v_add_f32_e32 v28, v47, v28
	v_mul_f32_e32 v53, v69, v69
	v_fmac_f32_e32 v51, v66, v66
	v_add_f32_e32 v28, v49, v28
	v_mul_f32_e32 v55, v71, v71
	v_fmac_f32_e32 v53, v68, v68
	v_add_f32_e32 v28, v51, v28
	v_mul_f32_e32 v57, v73, v73
	v_fmac_f32_e32 v55, v70, v70
	v_add_f32_e32 v28, v53, v28
	v_mul_f32_e32 v59, v75, v75
	v_fmac_f32_e32 v57, v72, v72
	v_add_f32_e32 v28, v55, v28
	v_mul_f32_e32 v61, v77, v77
	v_fmac_f32_e32 v59, v74, v74
	v_add_f32_e32 v28, v57, v28
	v_mul_f32_e32 v63, v79, v79
	v_fmac_f32_e32 v61, v76, v76
	v_add_f32_e32 v28, v59, v28
	v_mul_f32_e32 v65, v81, v81
	v_fmac_f32_e32 v63, v78, v78
	v_add_f32_e32 v28, v61, v28
	v_mul_f32_e32 v67, v83, v83
	v_fmac_f32_e32 v65, v80, v80
	v_add_f32_e32 v28, v63, v28
	v_mul_f32_e32 v69, v85, v85
	v_fmac_f32_e32 v67, v82, v82
	v_add_f32_e32 v28, v65, v28
	v_mul_f32_e32 v71, v87, v87
	v_fmac_f32_e32 v69, v84, v84
	v_add_f32_e32 v28, v67, v28
	v_fmac_f32_e32 v71, v86, v86
	v_add_f32_e32 v28, v69, v28
	v_add_f32_e32 v28, v71, v28
	v_add_f32_e32 v16, v16, v28
	v_add_f32_e32 v16, v17, v16
	v_pk_mul_f32 v[26:27], v[26:27], v[26:27]
	v_add_f32_e32 v16, v18, v16
	v_pk_fma_f32 v[20:21], v[24:25], v[24:25], v[26:27]
	v_add_f32_e32 v16, v19, v16
	v_add_f32_e32 v16, v20, v16
	v_add_f32_e32 v16, v21, v16
	v_pk_mul_f32 v[34:35], v[34:35], v[34:35]
	v_add_f32_e32 v16, v22, v16
	v_pk_fma_f32 v[24:25], v[32:33], v[32:33], v[34:35]
	v_add_f32_e32 v16, v23, v16
	v_pk_mul_f32 v[38:39], v[38:39], v[38:39]
	v_add_f32_e32 v16, v24, v16
	v_pk_fma_f32 v[26:27], v[36:37], v[36:37], v[38:39]
	v_add_f32_e32 v16, v25, v16
	v_add_f32_e32 v16, v26, v16
	v_add_f32_e32 v16, v27, v16
	v_max_f32_e32 v0, v0, v16
	ds_bpermute_b32 v2, v6, v0
	v_max_f32_e32 v0, v0, v0
	s_waitcnt lgkmcnt(0)
	v_max_f32_e32 v2, v2, v2
	v_max_f32_e32 v0, v0, v2
	ds_bpermute_b32 v2, v7, v0
	s_waitcnt lgkmcnt(0)
	v_max_f32_e32 v2, v2, v2
	v_max_f32_e32 v0, v0, v2
	ds_bpermute_b32 v2, v8, v0
	s_waitcnt lgkmcnt(0)
	v_max_f32_e32 v2, v2, v2
	v_max_f32_e32 v0, v0, v2
	ds_bpermute_b32 v2, v9, v0
	s_waitcnt lgkmcnt(0)
	v_max_f32_e32 v2, v2, v2
	v_max_f32_e32 v0, v0, v2
	ds_bpermute_b32 v2, v10, v0
	s_waitcnt lgkmcnt(0)
	v_max_f32_e32 v2, v2, v2
	v_max_f32_e32 v0, v0, v2
	ds_bpermute_b32 v2, v11, v0
	s_and_saveexec_b64 s[2:3], vcc
	s_cbranch_execz .LBB0_468
	v_ashrrev_i32_e32 v16, 2, v88
	v_readlane_b32 s52, v245, 49
	v_ashrrev_i32_e32 v17, 31, v16
	v_readlane_b32 s54, v245, 51
	v_readlane_b32 s55, v245, 52
	s_waitcnt lgkmcnt(0)
	v_max_f32_e32 v2, v2, v2
	v_max_f32_e32 v0, v0, v0
	v_lshl_add_u64 v[16:17], v[16:17], 2, s[54:55]
	v_max_f32_e32 v0, v0, v2
	global_atomic_umax v[16:17], v0, off
	v_readlane_b32 s53, v245, 50
	v_readlane_b32 s56, v245, 53
	v_readlane_b32 s57, v245, 54
	v_readlane_b32 s58, v245, 55
	v_readlane_b32 s59, v245, 56
	s_branch .LBB0_468
